# residual-GEMM epilogues (down-proj L0, out-proj/down-proj L1): first 14 of the 16 serialized residual reads hoisted into one register prefetch block; waits replaced by hazard nops
# speedup vs baseline: 1.0077x; 1.0077x over previous
; __device__ __forceinline__ unsigned cvt_pk_bf16(float lo, float hi) { unsigned r; asm volatile("v_cvt_pk_bf16_f32 %0, %1, %2" : "=v"(r) : "v"(lo), "v"(hi)); return r; }
; __device__ __forceinline__ float lo_f(unsigned w) { return __uint_as_float(w << 16); }
; __device__ __forceinline__ float hi_f(unsigned w) { return __uint_as_float(w & 0xffff0000u); }
;     __device__ __forceinline__ void operator()(f32x4 (&acc)[2][2][4][2], const Unit& u, int wr, int wc, int fr, int fq) const {
;         const int row0 = u.pm * BM + wr * 64 + fr, col0 = u.pn * BM + wc * 32 + 8 * fq;
;         const int r = u.pm < 32 ? (u.pm >> 3) : 4;
;         const float* gt = mod + (size_t)r * MODW + gate_off + col0;
;         f32x4 gv[2][2];
; #pragma unroll
;         for (int bj = 0; bj < 2; ++bj)
; #pragma unroll
;             for (int n = 0; n < 2; ++n) gv[bj][n] = *(const f32x4*)(gt + bj * HALF + 4 * n);
;         if (u.ks >= 0) {
;             float* pb = PART + ((size_t)u.ks * TC + (size_t)(row0 - TL)) * DM + col0;
; #pragma unroll
;             for (int ai = 0; ai < 2; ++ai)
; #pragma unroll
;                 for (int m = 0; m < 4; ++m)
; #pragma unroll
;                     for (int bj = 0; bj < 2; ++bj) { float* q = pb + (size_t)(ai * HALF + m * 16) * DM + bj * HALF;
;                         *(f32x4*)q = gv[bj][0] * acc[ai][bj][m][0]; *(f32x4*)(q + 4) = gv[bj][1] * acc[ai][bj][m][1]; }
;             return;
;         }
; #pragma unroll
;         for (int ai = 0; ai < 2; ++ai)
; #pragma unroll
;             for (int m = 0; m < 4; ++m) { const size_t ro = (size_t)(row0 + ai * HALF + m * 16) * DM + col0;
; #pragma unroll
;                 for (int bj = 0; bj < 2; ++bj) { f32x4 x0, x1;
;                     if (Xf32 != nullptr) { x0 = *(const f32x4*)(Xf32 + ro + bj * HALF); x1 = *(const f32x4*)(Xf32 + ro + bj * HALF + 4); }
;                     else { const u32x4 xb = *(const u32x4*)(X + ro + bj * HALF);
;                         x0 = (f32x4){lo_f(xb.x), hi_f(xb.x), lo_f(xb.y), hi_f(xb.y)}; x1 = (f32x4){lo_f(xb.z), hi_f(xb.z), lo_f(xb.w), hi_f(xb.w)}; }
;                     x0 += gv[bj][0] * acc[ai][bj][m][0]; x1 += gv[bj][1] * acc[ai][bj][m][1];
;                     u32x4 w; w.x = cvt_pk_bf16(x0[0], x0[1]); w.y = cvt_pk_bf16(x0[2], x0[3]); w.z = cvt_pk_bf16(x1[0], x1[1]); w.w = cvt_pk_bf16(x1[2], x1[3]);
;                     *(u32x4*)(X + ro + bj * HALF) = w; } }
.LBB0_1123:
	s_lshl_b64 s[34:35], s[34:35], 2
	v_lshl_or_b32 v158, s93, 8, v168
	s_add_u32 s34, s2, s34
	s_addc_u32 s35, s3, s35
	v_ashrrev_i32_e32 v159, 31, v158
	v_lshl_add_u64 v[128:129], v[158:159], 2, s[34:35]
	s_mov_b64 s[34:35], 0x1210a000
	v_lshl_add_u64 v[132:133], v[128:129], 0, s[34:35]
	s_mov_b32 s34, 0x1210a000
	v_add_co_u32_e32 v128, vcc, s34, v128
	v_lshl_add_u32 v160, s92, 8, v166
	s_nop 0
	v_addc_co_u32_e32 v129, vcc, 0, v129, vcc
	global_load_dwordx4 v[140:143], v[128:129], off
	s_nop 0
	global_load_dwordx4 v[128:131], v[132:133], off offset:528
	global_load_dwordx4 v[136:139], v[132:133], off offset:16
	s_nop 0
	global_load_dwordx4 v[132:135], v[132:133], off offset:512
	s_mov_b64 s[34:35], -1
	s_cmp_gt_i32 s6, -1
	v_ashrrev_i32_e32 v161, 31, v160
	s_cbranch_scc1 .LBB0_1126
	v_lshlrev_b64 v[162:163], 12, v[160:161]
	v_lshl_add_u64 v[162:163], s[10:11], 0, v[162:163]
	v_lshlrev_b64 v[164:165], 1, v[158:159]
	v_lshl_add_u64 v[162:163], v[162:163], 0, v[164:165]
	v_mov_b32_e32 v223, 0
	global_load_dwordx4 v[184:187], v[162:163], off
	global_load_dwordx4 v[188:191], v[162:163], off offset:256
	v_mov_b32_e32 v222, 0x10000
	v_lshl_add_u64 v[192:193], v[162:163], 0, v[222:223]
	global_load_dwordx4 v[196:199], v[192:193], off offset:256
	global_load_dwordx4 v[192:195], v[192:193], off
	v_mov_b32_e32 v222, 0x20000
	v_lshl_add_u64 v[200:201], v[162:163], 0, v[222:223]
	global_load_dwordx4 v[204:207], v[200:201], off offset:256
	global_load_dwordx4 v[200:203], v[200:201], off
	v_mov_b32_e32 v222, 0x30000
	v_lshl_add_u64 v[208:209], v[162:163], 0, v[222:223]
	global_load_dwordx4 v[212:215], v[208:209], off offset:256
	global_load_dwordx4 v[208:211], v[208:209], off
	v_mov_b32_e32 v222, 0x80000
	v_lshl_add_u64 v[218:219], v[162:163], 0, v[222:223]
	global_load_dwordx4 v[226:229], v[218:219], off offset:256
	global_load_dwordx4 v[218:221], v[218:219], off
	v_mov_b32_e32 v222, 0x90000
	v_lshl_add_u64 v[230:231], v[162:163], 0, v[222:223]
	global_load_dwordx4 v[234:237], v[230:231], off offset:256
	global_load_dwordx4 v[230:233], v[230:231], off
	v_mov_b32_e32 v222, 0xa0000
	v_lshl_add_u64 v[238:239], v[162:163], 0, v[222:223]
	global_load_dwordx4 v[242:245], v[238:239], off offset:256
	global_load_dwordx4 v[238:241], v[238:239], off
	v_or_b32_e32 v182, 32, v160
	v_ashrrev_i32_e32 v183, 31, v182
	v_lshlrev_b64 v[182:183], 12, v[182:183]
	v_lshl_add_u64 v[182:183], s[10:11], 0, v[182:183]
	v_lshl_add_u64 v[182:183], v[182:183], 0, v[164:165]
	s_waitcnt vmcnt(0)
	v_mov_b64_e32 v[172:173], v[184:185]
	v_mov_b64_e32 v[174:175], v[186:187]
	v_lshlrev_b32_e32 v176, 16, v172
	v_and_b32_e32 v177, 0xffff0000, v172
	v_lshlrev_b32_e32 v172, 16, v173
	v_and_b32_e32 v173, 0xffff0000, v173
	v_lshlrev_b32_e32 v178, 16, v174
	v_and_b32_e32 v179, 0xffff0000, v174
	v_lshlrev_b32_e32 v174, 16, v175
	v_and_b32_e32 v175, 0xffff0000, v175
	v_pk_fma_f32 v[180:181], v[126:127], v[142:143], v[172:173]
	v_pk_fma_f32 v[172:173], v[124:125], v[140:141], v[176:177]
	v_pk_fma_f32 v[176:177], v[122:123], v[138:139], v[174:175]
	v_pk_fma_f32 v[174:175], v[120:121], v[136:137], v[178:179]
	v_cvt_pk_bf16_f32 v172, v172, v173
	v_cvt_pk_bf16_f32 v173, v180, v181
	v_or_b32_e32 v180, 16, v160
	v_cvt_pk_bf16_f32 v174, v174, v175
	v_cvt_pk_bf16_f32 v175, v176, v177
	v_mov_b64_e32 v[176:177], v[188:189]
	v_mov_b64_e32 v[178:179], v[190:191]
	v_ashrrev_i32_e32 v181, 31, v180
	v_lshlrev_b64 v[180:181], 12, v[180:181]
	v_lshl_add_u64 v[180:181], s[10:11], 0, v[180:181]
	global_store_dwordx4 v[162:163], v[172:175], off
	v_lshl_add_u64 v[180:181], v[180:181], 0, v[164:165]
	s_nop 0
	v_lshlrev_b32_e32 v172, 16, v176
	v_and_b32_e32 v173, 0xffff0000, v176
	v_lshlrev_b32_e32 v174, 16, v177
	v_and_b32_e32 v175, 0xffff0000, v177
	v_lshlrev_b32_e32 v176, 16, v178
	v_and_b32_e32 v177, 0xffff0000, v178
	v_lshlrev_b32_e32 v178, 16, v179
	v_and_b32_e32 v179, 0xffff0000, v179
	v_pk_fma_f32 v[174:175], v[114:115], v[134:135], v[174:175]
	v_pk_fma_f32 v[172:173], v[112:113], v[132:133], v[172:173]
	v_pk_fma_f32 v[178:179], v[106:107], v[130:131], v[178:179]
	v_pk_fma_f32 v[176:177], v[104:105], v[128:129], v[176:177]
	v_cvt_pk_bf16_f32 v172, v172, v173
	v_cvt_pk_bf16_f32 v173, v174, v175
	s_nop 0
	v_cvt_pk_bf16_f32 v174, v176, v177
	v_cvt_pk_bf16_f32 v175, v178, v179
	v_mov_b64_e32 v[176:177], v[192:193]
	v_mov_b64_e32 v[178:179], v[194:195]
	s_nop 0
	global_store_dwordx4 v[162:163], v[172:175], off offset:256
	s_nop 0
	s_nop 0
	v_lshlrev_b32_e32 v172, 16, v176
	v_and_b32_e32 v173, 0xffff0000, v176
	v_lshlrev_b32_e32 v174, 16, v177
	v_and_b32_e32 v175, 0xffff0000, v177
	v_lshlrev_b32_e32 v176, 16, v178
	v_and_b32_e32 v177, 0xffff0000, v178
	v_lshlrev_b32_e32 v178, 16, v179
	v_and_b32_e32 v179, 0xffff0000, v179
	v_pk_fma_f32 v[174:175], v[118:119], v[142:143], v[174:175]
	v_pk_fma_f32 v[172:173], v[116:117], v[140:141], v[172:173]
	v_pk_fma_f32 v[178:179], v[110:111], v[138:139], v[178:179]
	v_pk_fma_f32 v[176:177], v[108:109], v[136:137], v[176:177]
	v_cvt_pk_bf16_f32 v172, v172, v173
	v_cvt_pk_bf16_f32 v173, v174, v175
	s_nop 0
	v_cvt_pk_bf16_f32 v174, v176, v177
	v_cvt_pk_bf16_f32 v175, v178, v179
	v_mov_b64_e32 v[176:177], v[196:197]
	v_mov_b64_e32 v[178:179], v[198:199]
	s_nop 0
	global_store_dwordx4 v[180:181], v[172:175], off
	s_nop 0
	s_nop 0
	v_lshlrev_b32_e32 v172, 16, v176
	v_and_b32_e32 v173, 0xffff0000, v176
	v_lshlrev_b32_e32 v174, 16, v177
	v_and_b32_e32 v175, 0xffff0000, v177
	v_lshlrev_b32_e32 v176, 16, v178
	v_and_b32_e32 v177, 0xffff0000, v178
	v_lshlrev_b32_e32 v178, 16, v179
	v_and_b32_e32 v179, 0xffff0000, v179
	v_pk_fma_f32 v[174:175], v[98:99], v[134:135], v[174:175]
; __device__ __forceinline__ unsigned cvt_pk_bf16(float lo, float hi) { unsigned r; asm volatile("v_cvt_pk_bf16_f32 %0, %1, %2" : "=v"(r) : "v"(lo), "v"(hi)); return r; }
; __device__ __forceinline__ float lo_f(unsigned w) { return __uint_as_float(w << 16); }
; __device__ __forceinline__ float hi_f(unsigned w) { return __uint_as_float(w & 0xffff0000u); }
;     __device__ __forceinline__ void operator()(f32x4 (&acc)[2][2][4][2], const Unit& u, int wr, int wc, int fr, int fq) const {
;     ...
; #pragma unroll
;         for (int ai = 0; ai < 2; ++ai)
; #pragma unroll
;             for (int m = 0; m < 4; ++m) { const size_t ro = (size_t)(row0 + ai * HALF + m * 16) * DM + col0;
; #pragma unroll
;                 for (int bj = 0; bj < 2; ++bj) { f32x4 x0, x1;
;                     if (Xf32 != nullptr) { x0 = *(const f32x4*)(Xf32 + ro + bj * HALF); x1 = *(const f32x4*)(Xf32 + ro + bj * HALF + 4); }
;                     else { const u32x4 xb = *(const u32x4*)(X + ro + bj * HALF);
;                         x0 = (f32x4){lo_f(xb.x), hi_f(xb.x), lo_f(xb.y), hi_f(xb.y)}; x1 = (f32x4){lo_f(xb.z), hi_f(xb.z), lo_f(xb.w), hi_f(xb.w)}; }
;                     x0 += gv[bj][0] * acc[ai][bj][m][0]; x1 += gv[bj][1] * acc[ai][bj][m][1];
;                     u32x4 w; w.x = cvt_pk_bf16(x0[0], x0[1]); w.y = cvt_pk_bf16(x0[2], x0[3]); w.z = cvt_pk_bf16(x1[0], x1[1]); w.w = cvt_pk_bf16(x1[2], x1[3]);
;                     *(u32x4*)(X + ro + bj * HALF) = w; } }
	v_pk_fma_f32 v[172:173], v[96:97], v[132:133], v[172:173]
	v_pk_fma_f32 v[178:179], v[90:91], v[130:131], v[178:179]
	v_pk_fma_f32 v[176:177], v[88:89], v[128:129], v[176:177]
	v_cvt_pk_bf16_f32 v172, v172, v173
	v_cvt_pk_bf16_f32 v173, v174, v175
	s_nop 0
	v_cvt_pk_bf16_f32 v174, v176, v177
	v_cvt_pk_bf16_f32 v175, v178, v179
	v_mov_b64_e32 v[176:177], v[200:201]
	v_mov_b64_e32 v[178:179], v[202:203]
	s_nop 0
	global_store_dwordx4 v[180:181], v[172:175], off offset:256
	v_or_b32_e32 v180, 48, v160
	v_ashrrev_i32_e32 v181, 31, v180
	v_lshlrev_b64 v[180:181], 12, v[180:181]
	v_lshl_add_u64 v[180:181], s[10:11], 0, v[180:181]
	v_lshl_add_u64 v[164:165], v[180:181], 0, v[164:165]
	v_add_co_u32_e32 v180, vcc, s68, v162
	s_nop 0
	v_lshlrev_b32_e32 v172, 16, v176
	v_and_b32_e32 v173, 0xffff0000, v176
	v_lshlrev_b32_e32 v174, 16, v177
	v_and_b32_e32 v175, 0xffff0000, v177
	v_lshlrev_b32_e32 v176, 16, v178
	v_and_b32_e32 v177, 0xffff0000, v178
	v_lshlrev_b32_e32 v178, 16, v179
	v_and_b32_e32 v179, 0xffff0000, v179
	v_pk_fma_f32 v[174:175], v[102:103], v[142:143], v[174:175]
	v_pk_fma_f32 v[172:173], v[100:101], v[140:141], v[172:173]
	v_pk_fma_f32 v[178:179], v[94:95], v[138:139], v[178:179]
	v_pk_fma_f32 v[176:177], v[92:93], v[136:137], v[176:177]
	v_cvt_pk_bf16_f32 v172, v172, v173
	v_cvt_pk_bf16_f32 v173, v174, v175
	v_addc_co_u32_e32 v181, vcc, 0, v163, vcc
	v_cvt_pk_bf16_f32 v174, v176, v177
	v_cvt_pk_bf16_f32 v175, v178, v179
	v_mov_b64_e32 v[176:177], v[204:205]
	v_mov_b64_e32 v[178:179], v[206:207]
	s_nop 0
	global_store_dwordx4 v[182:183], v[172:175], off
	s_nop 0
	s_nop 0
	v_lshlrev_b32_e32 v172, 16, v176
	v_and_b32_e32 v173, 0xffff0000, v176
	v_lshlrev_b32_e32 v174, 16, v177
	v_and_b32_e32 v175, 0xffff0000, v177
	v_lshlrev_b32_e32 v176, 16, v178
	v_and_b32_e32 v177, 0xffff0000, v178
	v_lshlrev_b32_e32 v178, 16, v179
	v_and_b32_e32 v179, 0xffff0000, v179
	v_pk_fma_f32 v[174:175], v[82:83], v[134:135], v[174:175]
	v_pk_fma_f32 v[172:173], v[80:81], v[132:133], v[172:173]
	v_pk_fma_f32 v[178:179], v[74:75], v[130:131], v[178:179]
	v_pk_fma_f32 v[176:177], v[72:73], v[128:129], v[176:177]
	v_cvt_pk_bf16_f32 v172, v172, v173
	v_cvt_pk_bf16_f32 v173, v174, v175
	s_nop 0
	v_cvt_pk_bf16_f32 v174, v176, v177
	v_cvt_pk_bf16_f32 v175, v178, v179
	v_mov_b64_e32 v[176:177], v[208:209]
	v_mov_b64_e32 v[178:179], v[210:211]
	s_nop 0
	global_store_dwordx4 v[182:183], v[172:175], off offset:256
	v_lshl_add_u64 v[182:183], v[162:163], 0, s[18:19]
	s_nop 0
	v_lshlrev_b32_e32 v172, 16, v176
	v_and_b32_e32 v173, 0xffff0000, v176
	v_lshlrev_b32_e32 v174, 16, v177
	v_and_b32_e32 v175, 0xffff0000, v177
	v_lshlrev_b32_e32 v176, 16, v178
	v_and_b32_e32 v177, 0xffff0000, v178
	v_lshlrev_b32_e32 v178, 16, v179
	v_and_b32_e32 v179, 0xffff0000, v179
	v_pk_fma_f32 v[174:175], v[86:87], v[142:143], v[174:175]
	v_pk_fma_f32 v[172:173], v[84:85], v[140:141], v[172:173]
	v_pk_fma_f32 v[178:179], v[78:79], v[138:139], v[178:179]
	v_pk_fma_f32 v[176:177], v[76:77], v[136:137], v[176:177]
	v_cvt_pk_bf16_f32 v172, v172, v173
	v_cvt_pk_bf16_f32 v173, v174, v175
	s_nop 0
	v_cvt_pk_bf16_f32 v174, v176, v177
	v_cvt_pk_bf16_f32 v175, v178, v179
	v_mov_b64_e32 v[176:177], v[212:213]
	v_mov_b64_e32 v[178:179], v[214:215]
	s_nop 0
	global_store_dwordx4 v[164:165], v[172:175], off
	s_nop 0
	s_nop 0
	v_lshlrev_b32_e32 v172, 16, v176
	v_and_b32_e32 v173, 0xffff0000, v176
	v_lshlrev_b32_e32 v174, 16, v177
	v_and_b32_e32 v175, 0xffff0000, v177
	v_lshlrev_b32_e32 v176, 16, v178
	v_and_b32_e32 v177, 0xffff0000, v178
	v_lshlrev_b32_e32 v178, 16, v179
	v_and_b32_e32 v179, 0xffff0000, v179
	v_pk_fma_f32 v[174:175], v[70:71], v[134:135], v[174:175]
	v_pk_fma_f32 v[172:173], v[68:69], v[132:133], v[172:173]
	v_pk_fma_f32 v[178:179], v[66:67], v[130:131], v[178:179]
	v_pk_fma_f32 v[176:177], v[64:65], v[128:129], v[176:177]
	v_cvt_pk_bf16_f32 v172, v172, v173
	v_cvt_pk_bf16_f32 v173, v174, v175
	s_nop 0
	v_cvt_pk_bf16_f32 v174, v176, v177
	v_cvt_pk_bf16_f32 v175, v178, v179
	v_mov_b64_e32 v[176:177], v[218:219]
	v_mov_b64_e32 v[178:179], v[220:221]
	s_nop 0
	global_store_dwordx4 v[164:165], v[172:175], off offset:256
	s_nop 0
	v_lshlrev_b32_e32 v164, 16, v176
	v_and_b32_e32 v165, 0xffff0000, v176
	v_lshlrev_b32_e32 v172, 16, v177
	v_and_b32_e32 v173, 0xffff0000, v177
	v_lshlrev_b32_e32 v174, 16, v178
	v_and_b32_e32 v175, 0xffff0000, v178
	v_lshlrev_b32_e32 v176, 16, v179
	v_and_b32_e32 v177, 0xffff0000, v179
	v_pk_fma_f32 v[178:179], v[62:63], v[142:143], v[172:173]
	v_pk_fma_f32 v[176:177], v[58:59], v[138:139], v[176:177]
	v_pk_fma_f32 v[174:175], v[56:57], v[136:137], v[174:175]
	v_pk_fma_f32 v[164:165], v[60:61], v[140:141], v[164:165]
	s_nop 0
	v_cvt_pk_bf16_f32 v172, v164, v165
	v_cvt_pk_bf16_f32 v173, v178, v179
	v_cvt_pk_bf16_f32 v174, v174, v175
	v_cvt_pk_bf16_f32 v175, v176, v177
	v_mov_b64_e32 v[176:177], v[226:227]
	v_mov_b64_e32 v[178:179], v[228:229]
	v_add_co_u32_e32 v164, vcc, s69, v162
	global_store_dwordx4 v[180:181], v[172:175], off
	s_nop 0
	v_addc_co_u32_e32 v165, vcc, 0, v163, vcc
	v_lshl_add_u64 v[180:181], v[162:163], 0, s[20:21]
	s_nop 0
	v_lshlrev_b32_e32 v172, 16, v176
	v_and_b32_e32 v173, 0xffff0000, v176
	v_lshlrev_b32_e32 v174, 16, v177
	v_and_b32_e32 v175, 0xffff0000, v177
	v_lshlrev_b32_e32 v176, 16, v178
	v_and_b32_e32 v177, 0xffff0000, v178
	v_lshlrev_b32_e32 v178, 16, v179
	v_and_b32_e32 v179, 0xffff0000, v179
	v_pk_fma_f32 v[174:175], v[50:51], v[134:135], v[174:175]
	v_pk_fma_f32 v[172:173], v[48:49], v[132:133], v[172:173]
; __device__ __forceinline__ unsigned cvt_pk_bf16(float lo, float hi) { unsigned r; asm volatile("v_cvt_pk_bf16_f32 %0, %1, %2" : "=v"(r) : "v"(lo), "v"(hi)); return r; }
; __device__ __forceinline__ float lo_f(unsigned w) { return __uint_as_float(w << 16); }
; __device__ __forceinline__ float hi_f(unsigned w) { return __uint_as_float(w & 0xffff0000u); }
;     __device__ __forceinline__ void operator()(f32x4 (&acc)[2][2][4][2], const Unit& u, int wr, int wc, int fr, int fq) const {
;     ...
; #pragma unroll
;         for (int ai = 0; ai < 2; ++ai)
; #pragma unroll
;             for (int m = 0; m < 4; ++m) { const size_t ro = (size_t)(row0 + ai * HALF + m * 16) * DM + col0;
; #pragma unroll
;                 for (int bj = 0; bj < 2; ++bj) { f32x4 x0, x1;
;                     if (Xf32 != nullptr) { x0 = *(const f32x4*)(Xf32 + ro + bj * HALF); x1 = *(const f32x4*)(Xf32 + ro + bj * HALF + 4); }
;                     else { const u32x4 xb = *(const u32x4*)(X + ro + bj * HALF);
;                         x0 = (f32x4){lo_f(xb.x), hi_f(xb.x), lo_f(xb.y), hi_f(xb.y)}; x1 = (f32x4){lo_f(xb.z), hi_f(xb.z), lo_f(xb.w), hi_f(xb.w)}; }
;                     x0 += gv[bj][0] * acc[ai][bj][m][0]; x1 += gv[bj][1] * acc[ai][bj][m][1];
;                     u32x4 w; w.x = cvt_pk_bf16(x0[0], x0[1]); w.y = cvt_pk_bf16(x0[2], x0[3]); w.z = cvt_pk_bf16(x1[0], x1[1]); w.w = cvt_pk_bf16(x1[2], x1[3]);
;                     *(u32x4*)(X + ro + bj * HALF) = w; } }
	v_pk_fma_f32 v[178:179], v[42:43], v[130:131], v[178:179]
	v_pk_fma_f32 v[176:177], v[40:41], v[128:129], v[176:177]
	v_cvt_pk_bf16_f32 v172, v172, v173
	v_cvt_pk_bf16_f32 v173, v174, v175
	s_nop 0
	v_cvt_pk_bf16_f32 v174, v176, v177
	v_cvt_pk_bf16_f32 v175, v178, v179
	v_mov_b64_e32 v[176:177], v[230:231]
	v_mov_b64_e32 v[178:179], v[232:233]
	s_nop 0
	global_store_dwordx4 v[182:183], v[172:175], off offset:256
	v_add_co_u32_e32 v182, vcc, s70, v162
	s_nop 0
	v_lshlrev_b32_e32 v172, 16, v176
	v_and_b32_e32 v173, 0xffff0000, v176
	v_lshlrev_b32_e32 v174, 16, v177
	v_and_b32_e32 v175, 0xffff0000, v177
	v_lshlrev_b32_e32 v176, 16, v178
	v_and_b32_e32 v177, 0xffff0000, v178
	v_lshlrev_b32_e32 v178, 16, v179
	v_and_b32_e32 v179, 0xffff0000, v179
	v_pk_fma_f32 v[174:175], v[54:55], v[142:143], v[174:175]
	v_pk_fma_f32 v[172:173], v[52:53], v[140:141], v[172:173]
	v_pk_fma_f32 v[178:179], v[46:47], v[138:139], v[178:179]
	v_pk_fma_f32 v[176:177], v[44:45], v[136:137], v[176:177]
	v_cvt_pk_bf16_f32 v172, v172, v173
	v_cvt_pk_bf16_f32 v173, v174, v175
	v_addc_co_u32_e32 v183, vcc, 0, v163, vcc
	v_cvt_pk_bf16_f32 v174, v176, v177
	v_cvt_pk_bf16_f32 v175, v178, v179
	v_mov_b64_e32 v[176:177], v[234:235]
	v_mov_b64_e32 v[178:179], v[236:237]
	s_nop 0
	global_store_dwordx4 v[164:165], v[172:175], off
	s_nop 0
	v_lshlrev_b32_e32 v164, 16, v176
	v_and_b32_e32 v165, 0xffff0000, v176
	v_lshlrev_b32_e32 v172, 16, v177
	v_and_b32_e32 v173, 0xffff0000, v177
	v_lshlrev_b32_e32 v174, 16, v178
	v_and_b32_e32 v175, 0xffff0000, v178
	v_lshlrev_b32_e32 v176, 16, v179
	v_and_b32_e32 v177, 0xffff0000, v179
	v_pk_fma_f32 v[178:179], v[34:35], v[134:135], v[172:173]
	v_pk_fma_f32 v[176:177], v[26:27], v[130:131], v[176:177]
	v_pk_fma_f32 v[174:175], v[24:25], v[128:129], v[174:175]
	v_pk_fma_f32 v[164:165], v[32:33], v[132:133], v[164:165]
	s_nop 0
	v_cvt_pk_bf16_f32 v172, v164, v165
	v_cvt_pk_bf16_f32 v173, v178, v179
	v_cvt_pk_bf16_f32 v174, v174, v175
	v_cvt_pk_bf16_f32 v175, v176, v177
	v_mov_b64_e32 v[176:177], v[238:239]
	v_mov_b64_e32 v[178:179], v[240:241]
	v_lshl_add_u64 v[164:165], v[162:163], 0, s[22:23]
	global_store_dwordx4 v[180:181], v[172:175], off offset:256
	v_add_co_u32_e32 v180, vcc, s71, v162
	s_nop 0
	v_lshlrev_b32_e32 v172, 16, v176
	v_and_b32_e32 v173, 0xffff0000, v176
	v_lshlrev_b32_e32 v174, 16, v177
	v_and_b32_e32 v175, 0xffff0000, v177
	v_lshlrev_b32_e32 v176, 16, v178
	v_and_b32_e32 v177, 0xffff0000, v178
	v_lshlrev_b32_e32 v178, 16, v179
	v_and_b32_e32 v179, 0xffff0000, v179
	v_pk_fma_f32 v[174:175], v[38:39], v[142:143], v[174:175]
	v_pk_fma_f32 v[172:173], v[36:37], v[140:141], v[172:173]
	v_pk_fma_f32 v[178:179], v[30:31], v[138:139], v[178:179]
	v_pk_fma_f32 v[176:177], v[28:29], v[136:137], v[176:177]
	v_cvt_pk_bf16_f32 v172, v172, v173
	v_cvt_pk_bf16_f32 v173, v174, v175
	v_addc_co_u32_e32 v181, vcc, 0, v163, vcc
	v_cvt_pk_bf16_f32 v174, v176, v177
	v_cvt_pk_bf16_f32 v175, v178, v179
	v_mov_b64_e32 v[176:177], v[242:243]
	v_mov_b64_e32 v[178:179], v[244:245]
	s_nop 0
	global_store_dwordx4 v[182:183], v[172:175], off
	v_lshl_add_u64 v[182:183], v[162:163], 0, s[24:25]
	s_nop 0
	v_lshlrev_b32_e32 v172, 16, v176
	v_and_b32_e32 v173, 0xffff0000, v176
	v_lshlrev_b32_e32 v174, 16, v177
	v_and_b32_e32 v175, 0xffff0000, v177
	v_lshlrev_b32_e32 v176, 16, v178
	v_and_b32_e32 v177, 0xffff0000, v178
	v_lshlrev_b32_e32 v178, 16, v179
	v_and_b32_e32 v179, 0xffff0000, v179
	v_pk_fma_f32 v[174:175], v[18:19], v[134:135], v[174:175]
	v_pk_fma_f32 v[172:173], v[16:17], v[132:133], v[172:173]
	v_pk_fma_f32 v[178:179], v[10:11], v[130:131], v[178:179]
	v_pk_fma_f32 v[176:177], v[8:9], v[128:129], v[176:177]
	v_cvt_pk_bf16_f32 v172, v172, v173
	v_cvt_pk_bf16_f32 v173, v174, v175
	s_nop 0
	v_cvt_pk_bf16_f32 v174, v176, v177
	v_cvt_pk_bf16_f32 v175, v178, v179
	global_load_dwordx4 v[176:179], v[180:181], off
	s_waitcnt vmcnt(0)
	v_lshlrev_b32_e32 v162, 16, v176
	global_store_dwordx4 v[164:165], v[172:175], off offset:256
	v_and_b32_e32 v163, 0xffff0000, v176
	v_lshlrev_b32_e32 v164, 16, v177
	v_and_b32_e32 v165, 0xffff0000, v177
	v_lshlrev_b32_e32 v172, 16, v178
	v_and_b32_e32 v173, 0xffff0000, v178
	v_lshlrev_b32_e32 v174, 16, v179
	v_and_b32_e32 v175, 0xffff0000, v179
	v_pk_fma_f32 v[164:165], v[22:23], v[142:143], v[164:165]
	v_pk_fma_f32 v[162:163], v[20:21], v[140:141], v[162:163]
	v_pk_fma_f32 v[174:175], v[14:15], v[138:139], v[174:175]
	v_pk_fma_f32 v[172:173], v[12:13], v[136:137], v[172:173]
	v_cvt_pk_bf16_f32 v162, v162, v163
	v_cvt_pk_bf16_f32 v163, v164, v165
	s_nop 0
	v_cvt_pk_bf16_f32 v164, v172, v173
	v_cvt_pk_bf16_f32 v165, v174, v175
	global_load_dwordx4 v[172:175], v[182:183], off offset:256
	s_nop 0
	global_store_dwordx4 v[180:181], v[162:165], off
	s_waitcnt vmcnt(1)
	s_nop 0
	v_lshlrev_b32_e32 v162, 16, v172
	v_and_b32_e32 v163, 0xffff0000, v172
	v_lshlrev_b32_e32 v164, 16, v173
	v_and_b32_e32 v165, 0xffff0000, v173
	v_lshlrev_b32_e32 v172, 16, v174
	v_and_b32_e32 v173, 0xffff0000, v174
	v_lshlrev_b32_e32 v174, 16, v175
	v_and_b32_e32 v175, 0xffff0000, v175
	v_pk_fma_f32 v[164:165], v[6:7], v[134:135], v[164:165]
	v_pk_fma_f32 v[162:163], v[4:5], v[132:133], v[162:163]
	v_pk_fma_f32 v[174:175], v[2:3], v[130:131], v[174:175]
	v_pk_fma_f32 v[172:173], v[0:1], v[128:129], v[172:173]
	v_cvt_pk_bf16_f32 v162, v162, v163
	v_cvt_pk_bf16_f32 v163, v164, v165
	s_nop 0
	v_cvt_pk_bf16_f32 v164, v172, v173
	v_cvt_pk_bf16_f32 v165, v174, v175
	global_store_dwordx4 v[182:183], v[162:165], off offset:256
	s_cbranch_execz .LBB0_1127

; __device__ __forceinline__ unsigned cvt_pk_bf16(float lo, float hi) { unsigned r; asm volatile("v_cvt_pk_bf16_f32 %0, %1, %2" : "=v"(r) : "v"(lo), "v"(hi)); return r; }
; __device__ __forceinline__ float lo_f(unsigned w) { return __uint_as_float(w << 16); }
; __device__ __forceinline__ float hi_f(unsigned w) { return __uint_as_float(w & 0xffff0000u); }
;     __device__ __forceinline__ void operator()(f32x4 (&acc)[2][2][4][2], const Unit& u, int wr, int wc, int fr, int fq) const {
;         const int row0 = u.pm * BM + wr * 64 + fr, col0 = u.pn * BM + wc * 32 + 8 * fq;
;         const int r = u.pm < 32 ? (u.pm >> 3) : 4;
;         const float* gt = mod + (size_t)r * MODW + gate_off + col0;
;         f32x4 gv[2][2];
; #pragma unroll
;         for (int bj = 0; bj < 2; ++bj)
; #pragma unroll
;             for (int n = 0; n < 2; ++n) gv[bj][n] = *(const f32x4*)(gt + bj * HALF + 4 * n);
;         if (u.ks >= 0) {
;             float* pb = PART + ((size_t)u.ks * TC + (size_t)(row0 - TL)) * DM + col0;
; #pragma unroll
;             for (int ai = 0; ai < 2; ++ai)
; #pragma unroll
;                 for (int m = 0; m < 4; ++m)
; #pragma unroll
;                     for (int bj = 0; bj < 2; ++bj) { float* q = pb + (size_t)(ai * HALF + m * 16) * DM + bj * HALF;
;                         *(f32x4*)q = gv[bj][0] * acc[ai][bj][m][0]; *(f32x4*)(q + 4) = gv[bj][1] * acc[ai][bj][m][1]; }
;             return;
;         }
; #pragma unroll
;         for (int ai = 0; ai < 2; ++ai)
; #pragma unroll
;             for (int m = 0; m < 4; ++m) { const size_t ro = (size_t)(row0 + ai * HALF + m * 16) * DM + col0;
; #pragma unroll
;                 for (int bj = 0; bj < 2; ++bj) { f32x4 x0, x1;
;                     if (Xf32 != nullptr) { x0 = *(const f32x4*)(Xf32 + ro + bj * HALF); x1 = *(const f32x4*)(Xf32 + ro + bj * HALF + 4); }
;                     else { const u32x4 xb = *(const u32x4*)(X + ro + bj * HALF);
;                         x0 = (f32x4){lo_f(xb.x), hi_f(xb.x), lo_f(xb.y), hi_f(xb.y)}; x1 = (f32x4){lo_f(xb.z), hi_f(xb.z), lo_f(xb.w), hi_f(xb.w)}; }
;                     x0 += gv[bj][0] * acc[ai][bj][m][0]; x1 += gv[bj][1] * acc[ai][bj][m][1];
;                     u32x4 w; w.x = cvt_pk_bf16(x0[0], x0[1]); w.y = cvt_pk_bf16(x0[2], x0[3]); w.z = cvt_pk_bf16(x1[0], x1[1]); w.w = cvt_pk_bf16(x1[2], x1[3]);
;                     *(u32x4*)(X + ro + bj * HALF) = w; } }
.LBB0_1695:
	v_lshl_add_u32 v160, s36, 8, v164
	s_lshl_b64 s[42:43], s[42:43], 2
	v_lshl_or_b32 v120, s70, 8, v166
	s_add_u32 s42, s2, s42
	v_ashrrev_i32_e32 v161, 31, v160
	v_ashrrev_i32_e32 v121, 31, v120
	v_lshlrev_b64 v[122:123], 12, v[160:161]
	s_addc_u32 s43, s3, s43
	v_lshl_add_u64 v[122:123], s[8:9], 0, v[122:123]
	v_lshlrev_b64 v[162:163], 1, v[120:121]
	v_lshl_add_u64 v[120:121], v[120:121], 2, s[42:43]
	v_lshl_add_u64 v[158:159], v[122:123], 0, v[162:163]
	v_add_co_u32_e32 v122, vcc, s65, v120
	v_mov_b32_e32 v243, 0
	global_load_dwordx4 v[178:181], v[158:159], off
	global_load_dwordx4 v[182:185], v[158:159], off offset:256
	v_mov_b32_e32 v242, 0x10000
	v_lshl_add_u64 v[186:187], v[158:159], 0, v[242:243]
	global_load_dwordx4 v[190:193], v[186:187], off offset:256
	global_load_dwordx4 v[186:189], v[186:187], off
	v_mov_b32_e32 v242, 0x20000
	v_lshl_add_u64 v[194:195], v[158:159], 0, v[242:243]
	global_load_dwordx4 v[198:201], v[194:195], off offset:256
	global_load_dwordx4 v[194:197], v[194:195], off
	v_mov_b32_e32 v242, 0x30000
	v_lshl_add_u64 v[202:203], v[158:159], 0, v[242:243]
	global_load_dwordx4 v[206:209], v[202:203], off offset:256
	global_load_dwordx4 v[202:205], v[202:203], off
	v_mov_b32_e32 v242, 0x80000
	v_lshl_add_u64 v[210:211], v[158:159], 0, v[242:243]
	global_load_dwordx4 v[218:221], v[210:211], off offset:256
	global_load_dwordx4 v[210:213], v[210:211], off
	v_mov_b32_e32 v242, 0x90000
	v_lshl_add_u64 v[226:227], v[158:159], 0, v[242:243]
	global_load_dwordx4 v[230:233], v[226:227], off offset:256
	global_load_dwordx4 v[226:229], v[226:227], off
	v_mov_b32_e32 v242, 0xa0000
	v_lshl_add_u64 v[234:235], v[158:159], 0, v[242:243]
	global_load_dwordx4 v[238:241], v[234:235], off offset:256
	global_load_dwordx4 v[234:237], v[234:235], off
	s_nop 0
	v_addc_co_u32_e32 v123, vcc, 0, v121, vcc
	global_load_dwordx4 v[132:135], v[122:123], off
	v_lshl_add_u64 v[124:125], v[120:121], 0, s[16:17]
	global_load_dwordx4 v[128:131], v[124:125], off offset:16
	global_load_dwordx4 v[120:123], v[124:125], off offset:528
	s_nop 0
	global_load_dwordx4 v[124:127], v[124:125], off offset:512
	s_waitcnt vmcnt(0)
	v_mov_b64_e32 v[170:171], v[178:179]
	v_mov_b64_e32 v[172:173], v[180:181]
	v_lshlrev_b32_e32 v174, 16, v170
	v_and_b32_e32 v175, 0xffff0000, v170
	v_lshlrev_b32_e32 v170, 16, v171
	v_and_b32_e32 v171, 0xffff0000, v171
	v_lshlrev_b32_e32 v176, 16, v172
	v_and_b32_e32 v177, 0xffff0000, v172
	v_lshlrev_b32_e32 v172, 16, v173
	v_and_b32_e32 v173, 0xffff0000, v173
	v_pk_fma_f32 v[142:143], v[142:143], v[134:135], v[170:171]
	v_pk_fma_f32 v[140:141], v[140:141], v[132:133], v[174:175]
	v_pk_fma_f32 v[170:171], v[138:139], v[130:131], v[172:173]
	v_pk_fma_f32 v[138:139], v[136:137], v[128:129], v[176:177]
	v_cvt_pk_bf16_f32 v136, v140, v141
	v_cvt_pk_bf16_f32 v137, v142, v143
	s_nop 0
	v_cvt_pk_bf16_f32 v138, v138, v139
	v_cvt_pk_bf16_f32 v139, v170, v171
	v_mov_b64_e32 v[140:141], v[182:183]
	v_mov_b64_e32 v[142:143], v[184:185]
	v_or_b32_e32 v170, 16, v160
	v_ashrrev_i32_e32 v171, 31, v170
	v_lshlrev_b64 v[170:171], 12, v[170:171]
	v_lshl_add_u64 v[170:171], s[8:9], 0, v[170:171]
	global_store_dwordx4 v[158:159], v[136:139], off
	v_lshl_add_u64 v[170:171], v[170:171], 0, v[162:163]
	s_nop 0
	v_lshlrev_b32_e32 v136, 16, v140
	v_and_b32_e32 v137, 0xffff0000, v140
	v_lshlrev_b32_e32 v138, 16, v141
	v_and_b32_e32 v139, 0xffff0000, v141
	v_lshlrev_b32_e32 v140, 16, v142
	v_and_b32_e32 v141, 0xffff0000, v142
	v_lshlrev_b32_e32 v142, 16, v143
	v_and_b32_e32 v143, 0xffff0000, v143
	v_pk_fma_f32 v[114:115], v[114:115], v[126:127], v[138:139]
	v_pk_fma_f32 v[112:113], v[112:113], v[124:125], v[136:137]
	v_pk_fma_f32 v[136:137], v[110:111], v[122:123], v[142:143]
	v_pk_fma_f32 v[110:111], v[108:109], v[120:121], v[140:141]
	v_cvt_pk_bf16_f32 v108, v112, v113
	v_cvt_pk_bf16_f32 v109, v114, v115
	s_nop 0
	v_cvt_pk_bf16_f32 v110, v110, v111
	v_cvt_pk_bf16_f32 v111, v136, v137
	v_mov_b64_e32 v[112:113], v[186:187]
	v_mov_b64_e32 v[114:115], v[188:189]
	s_nop 0
	global_store_dwordx4 v[158:159], v[108:111], off offset:256
	s_nop 0
	s_nop 0
	v_lshlrev_b32_e32 v108, 16, v112
	v_and_b32_e32 v109, 0xffff0000, v112
	v_lshlrev_b32_e32 v110, 16, v113
	v_and_b32_e32 v111, 0xffff0000, v113
	v_lshlrev_b32_e32 v112, 16, v114
	v_and_b32_e32 v113, 0xffff0000, v114
	v_lshlrev_b32_e32 v114, 16, v115
	v_and_b32_e32 v115, 0xffff0000, v115
	v_pk_fma_f32 v[110:111], v[118:119], v[134:135], v[110:111]
	v_pk_fma_f32 v[108:109], v[116:117], v[132:133], v[108:109]
	v_pk_fma_f32 v[114:115], v[106:107], v[130:131], v[114:115]
	v_pk_fma_f32 v[106:107], v[104:105], v[128:129], v[112:113]
	v_cvt_pk_bf16_f32 v104, v108, v109
	v_cvt_pk_bf16_f32 v105, v110, v111
	v_or_b32_e32 v112, 32, v160
	v_cvt_pk_bf16_f32 v106, v106, v107
	v_cvt_pk_bf16_f32 v107, v114, v115
	v_mov_b64_e32 v[108:109], v[190:191]
	v_mov_b64_e32 v[110:111], v[192:193]
	v_ashrrev_i32_e32 v113, 31, v112
	v_lshlrev_b64 v[112:113], 12, v[112:113]
	v_lshl_add_u64 v[112:113], s[8:9], 0, v[112:113]
	global_store_dwordx4 v[170:171], v[104:107], off
	v_lshl_add_u64 v[112:113], v[112:113], 0, v[162:163]
	s_nop 0
	v_lshlrev_b32_e32 v104, 16, v108
	v_and_b32_e32 v105, 0xffff0000, v108
	v_lshlrev_b32_e32 v106, 16, v109
	v_and_b32_e32 v107, 0xffff0000, v109
	v_lshlrev_b32_e32 v108, 16, v110
	v_and_b32_e32 v109, 0xffff0000, v110
	v_lshlrev_b32_e32 v110, 16, v111
	v_and_b32_e32 v111, 0xffff0000, v111
	v_pk_fma_f32 v[98:99], v[98:99], v[126:127], v[106:107]
	v_pk_fma_f32 v[96:97], v[96:97], v[124:125], v[104:105]
	v_pk_fma_f32 v[104:105], v[94:95], v[122:123], v[110:111]
	v_pk_fma_f32 v[94:95], v[92:93], v[120:121], v[108:109]
; __device__ __forceinline__ unsigned cvt_pk_bf16(float lo, float hi) { unsigned r; asm volatile("v_cvt_pk_bf16_f32 %0, %1, %2" : "=v"(r) : "v"(lo), "v"(hi)); return r; }
; __device__ __forceinline__ float lo_f(unsigned w) { return __uint_as_float(w << 16); }
; __device__ __forceinline__ float hi_f(unsigned w) { return __uint_as_float(w & 0xffff0000u); }
;     __device__ __forceinline__ void operator()(f32x4 (&acc)[2][2][4][2], const Unit& u, int wr, int wc, int fr, int fq) const {
;     ...
; #pragma unroll
;         for (int ai = 0; ai < 2; ++ai)
; #pragma unroll
;             for (int m = 0; m < 4; ++m) { const size_t ro = (size_t)(row0 + ai * HALF + m * 16) * DM + col0;
; #pragma unroll
;                 for (int bj = 0; bj < 2; ++bj) { f32x4 x0, x1;
;                     if (Xf32 != nullptr) { x0 = *(const f32x4*)(Xf32 + ro + bj * HALF); x1 = *(const f32x4*)(Xf32 + ro + bj * HALF + 4); }
;                     else { const u32x4 xb = *(const u32x4*)(X + ro + bj * HALF);
;                         x0 = (f32x4){lo_f(xb.x), hi_f(xb.x), lo_f(xb.y), hi_f(xb.y)}; x1 = (f32x4){lo_f(xb.z), hi_f(xb.z), lo_f(xb.w), hi_f(xb.w)}; }
;                     x0 += gv[bj][0] * acc[ai][bj][m][0]; x1 += gv[bj][1] * acc[ai][bj][m][1];
;                     u32x4 w; w.x = cvt_pk_bf16(x0[0], x0[1]); w.y = cvt_pk_bf16(x0[2], x0[3]); w.z = cvt_pk_bf16(x1[0], x1[1]); w.w = cvt_pk_bf16(x1[2], x1[3]);
;                     *(u32x4*)(X + ro + bj * HALF) = w; } }
	v_cvt_pk_bf16_f32 v92, v96, v97
	v_cvt_pk_bf16_f32 v93, v98, v99
	s_nop 0
	v_cvt_pk_bf16_f32 v94, v94, v95
	v_cvt_pk_bf16_f32 v95, v104, v105
	v_mov_b64_e32 v[96:97], v[194:195]
	v_mov_b64_e32 v[98:99], v[196:197]
	s_nop 0
	global_store_dwordx4 v[170:171], v[92:95], off offset:256
	s_nop 0
	s_nop 0
	v_lshlrev_b32_e32 v92, 16, v96
	v_and_b32_e32 v93, 0xffff0000, v96
	v_lshlrev_b32_e32 v94, 16, v97
	v_and_b32_e32 v95, 0xffff0000, v97
	v_lshlrev_b32_e32 v96, 16, v98
	v_and_b32_e32 v97, 0xffff0000, v98
	v_lshlrev_b32_e32 v98, 16, v99
	v_and_b32_e32 v99, 0xffff0000, v99
	v_pk_fma_f32 v[94:95], v[102:103], v[134:135], v[94:95]
	v_pk_fma_f32 v[92:93], v[100:101], v[132:133], v[92:93]
	v_pk_fma_f32 v[98:99], v[90:91], v[130:131], v[98:99]
	v_pk_fma_f32 v[90:91], v[88:89], v[128:129], v[96:97]
	v_cvt_pk_bf16_f32 v88, v92, v93
	v_cvt_pk_bf16_f32 v89, v94, v95
	v_or_b32_e32 v96, 48, v160
	v_cvt_pk_bf16_f32 v90, v90, v91
	v_cvt_pk_bf16_f32 v91, v98, v99
	v_mov_b64_e32 v[92:93], v[198:199]
	v_mov_b64_e32 v[94:95], v[200:201]
	v_ashrrev_i32_e32 v97, 31, v96
	v_lshlrev_b64 v[96:97], 12, v[96:97]
	v_lshl_add_u64 v[96:97], s[8:9], 0, v[96:97]
	global_store_dwordx4 v[112:113], v[88:91], off
	v_lshl_add_u64 v[96:97], v[96:97], 0, v[162:163]
	s_nop 0
	v_lshlrev_b32_e32 v88, 16, v92
	v_and_b32_e32 v89, 0xffff0000, v92
	v_lshlrev_b32_e32 v90, 16, v93
	v_and_b32_e32 v91, 0xffff0000, v93
	v_lshlrev_b32_e32 v92, 16, v94
	v_and_b32_e32 v93, 0xffff0000, v94
	v_lshlrev_b32_e32 v94, 16, v95
	v_and_b32_e32 v95, 0xffff0000, v95
	v_pk_fma_f32 v[82:83], v[82:83], v[126:127], v[90:91]
	v_pk_fma_f32 v[80:81], v[80:81], v[124:125], v[88:89]
	v_pk_fma_f32 v[88:89], v[78:79], v[122:123], v[94:95]
	v_pk_fma_f32 v[78:79], v[76:77], v[120:121], v[92:93]
	v_cvt_pk_bf16_f32 v76, v80, v81
	v_cvt_pk_bf16_f32 v77, v82, v83
	s_nop 0
	v_cvt_pk_bf16_f32 v78, v78, v79
	v_cvt_pk_bf16_f32 v79, v88, v89
	v_mov_b64_e32 v[80:81], v[202:203]
	v_mov_b64_e32 v[82:83], v[204:205]
	s_nop 0
	global_store_dwordx4 v[112:113], v[76:79], off offset:256
	s_nop 0
	s_nop 0
	v_lshlrev_b32_e32 v76, 16, v80
	v_and_b32_e32 v77, 0xffff0000, v80
	v_lshlrev_b32_e32 v78, 16, v81
	v_and_b32_e32 v79, 0xffff0000, v81
	v_lshlrev_b32_e32 v80, 16, v82
	v_and_b32_e32 v81, 0xffff0000, v82
	v_lshlrev_b32_e32 v82, 16, v83
	v_and_b32_e32 v83, 0xffff0000, v83
	v_pk_fma_f32 v[78:79], v[86:87], v[134:135], v[78:79]
	v_pk_fma_f32 v[76:77], v[84:85], v[132:133], v[76:77]
	v_pk_fma_f32 v[82:83], v[74:75], v[130:131], v[82:83]
	v_pk_fma_f32 v[74:75], v[72:73], v[128:129], v[80:81]
	v_cvt_pk_bf16_f32 v72, v76, v77
	v_cvt_pk_bf16_f32 v73, v78, v79
	v_add_co_u32_e32 v80, vcc, s66, v158
	v_cvt_pk_bf16_f32 v74, v74, v75
	v_cvt_pk_bf16_f32 v75, v82, v83
	v_mov_b64_e32 v[76:77], v[206:207]
	v_mov_b64_e32 v[78:79], v[208:209]
	s_nop 0
	v_addc_co_u32_e32 v81, vcc, 0, v159, vcc
	global_store_dwordx4 v[96:97], v[72:75], off
	s_nop 0
	s_nop 0
	v_lshlrev_b32_e32 v72, 16, v76
	v_and_b32_e32 v73, 0xffff0000, v76
	v_lshlrev_b32_e32 v74, 16, v77
	v_and_b32_e32 v75, 0xffff0000, v77
	v_lshlrev_b32_e32 v76, 16, v78
	v_and_b32_e32 v77, 0xffff0000, v78
	v_lshlrev_b32_e32 v78, 16, v79
	v_and_b32_e32 v79, 0xffff0000, v79
	v_pk_fma_f32 v[70:71], v[70:71], v[126:127], v[74:75]
	v_pk_fma_f32 v[68:69], v[68:69], v[124:125], v[72:73]
	v_pk_fma_f32 v[72:73], v[66:67], v[122:123], v[78:79]
	v_pk_fma_f32 v[66:67], v[64:65], v[120:121], v[76:77]
	v_cvt_pk_bf16_f32 v64, v68, v69
	v_cvt_pk_bf16_f32 v65, v70, v71
	s_nop 0
	v_cvt_pk_bf16_f32 v66, v66, v67
	v_cvt_pk_bf16_f32 v67, v72, v73
	v_mov_b64_e32 v[68:69], v[210:211]
	v_mov_b64_e32 v[70:71], v[212:213]
	v_lshl_add_u64 v[72:73], v[158:159], 0, s[4:5]
	global_store_dwordx4 v[96:97], v[64:67], off offset:256
	s_nop 0
	s_nop 0
	v_lshlrev_b32_e32 v64, 16, v68
	v_and_b32_e32 v65, 0xffff0000, v68
	v_lshlrev_b32_e32 v66, 16, v69
	v_and_b32_e32 v67, 0xffff0000, v69
	v_lshlrev_b32_e32 v68, 16, v70
	v_and_b32_e32 v69, 0xffff0000, v70
	v_lshlrev_b32_e32 v70, 16, v71
	v_and_b32_e32 v71, 0xffff0000, v71
	v_pk_fma_f32 v[62:63], v[62:63], v[134:135], v[66:67]
	v_pk_fma_f32 v[60:61], v[60:61], v[132:133], v[64:65]
	v_pk_fma_f32 v[64:65], v[58:59], v[130:131], v[70:71]
	v_pk_fma_f32 v[58:59], v[56:57], v[128:129], v[68:69]
	v_cvt_pk_bf16_f32 v56, v60, v61
	v_cvt_pk_bf16_f32 v57, v62, v63
	s_nop 0
	v_cvt_pk_bf16_f32 v58, v58, v59
	v_cvt_pk_bf16_f32 v59, v64, v65
	v_mov_b64_e32 v[60:61], v[218:219]
	v_mov_b64_e32 v[62:63], v[220:221]
	v_add_co_u32_e32 v64, vcc, s67, v158
	global_store_dwordx4 v[80:81], v[56:59], off
	s_nop 0
	v_addc_co_u32_e32 v65, vcc, 0, v159, vcc
	s_nop 0
	v_lshlrev_b32_e32 v56, 16, v60
	v_and_b32_e32 v57, 0xffff0000, v60
	v_lshlrev_b32_e32 v58, 16, v61
	v_and_b32_e32 v59, 0xffff0000, v61
	v_lshlrev_b32_e32 v60, 16, v62
	v_and_b32_e32 v61, 0xffff0000, v62
	v_lshlrev_b32_e32 v62, 16, v63
	v_and_b32_e32 v63, 0xffff0000, v63
	v_pk_fma_f32 v[54:55], v[54:55], v[126:127], v[58:59]
	v_pk_fma_f32 v[52:53], v[52:53], v[124:125], v[56:57]
	v_pk_fma_f32 v[56:57], v[46:47], v[122:123], v[62:63]
	v_pk_fma_f32 v[46:47], v[44:45], v[120:121], v[60:61]
	v_cvt_pk_bf16_f32 v44, v52, v53
	v_cvt_pk_bf16_f32 v45, v54, v55
	s_nop 0
	v_cvt_pk_bf16_f32 v46, v46, v47
; __device__ __forceinline__ unsigned cvt_pk_bf16(float lo, float hi) { unsigned r; asm volatile("v_cvt_pk_bf16_f32 %0, %1, %2" : "=v"(r) : "v"(lo), "v"(hi)); return r; }
; __device__ __forceinline__ float lo_f(unsigned w) { return __uint_as_float(w << 16); }
; __device__ __forceinline__ float hi_f(unsigned w) { return __uint_as_float(w & 0xffff0000u); }
;     __device__ __forceinline__ void operator()(f32x4 (&acc)[2][2][4][2], const Unit& u, int wr, int wc, int fr, int fq) const {
;     ...
; #pragma unroll
;         for (int ai = 0; ai < 2; ++ai)
; #pragma unroll
;             for (int m = 0; m < 4; ++m) { const size_t ro = (size_t)(row0 + ai * HALF + m * 16) * DM + col0;
; #pragma unroll
;                 for (int bj = 0; bj < 2; ++bj) { f32x4 x0, x1;
;                     if (Xf32 != nullptr) { x0 = *(const f32x4*)(Xf32 + ro + bj * HALF); x1 = *(const f32x4*)(Xf32 + ro + bj * HALF + 4); }
;                     else { const u32x4 xb = *(const u32x4*)(X + ro + bj * HALF);
;                         x0 = (f32x4){lo_f(xb.x), hi_f(xb.x), lo_f(xb.y), hi_f(xb.y)}; x1 = (f32x4){lo_f(xb.z), hi_f(xb.z), lo_f(xb.w), hi_f(xb.w)}; }
;                     x0 += gv[bj][0] * acc[ai][bj][m][0]; x1 += gv[bj][1] * acc[ai][bj][m][1];
;                     u32x4 w; w.x = cvt_pk_bf16(x0[0], x0[1]); w.y = cvt_pk_bf16(x0[2], x0[3]); w.z = cvt_pk_bf16(x1[0], x1[1]); w.w = cvt_pk_bf16(x1[2], x1[3]);
;                     *(u32x4*)(X + ro + bj * HALF) = w; } }
	v_cvt_pk_bf16_f32 v47, v56, v57
	v_mov_b64_e32 v[52:53], v[226:227]
	v_mov_b64_e32 v[54:55], v[228:229]
	v_lshl_add_u64 v[56:57], v[158:159], 0, s[18:19]
	global_store_dwordx4 v[72:73], v[44:47], off offset:256
	s_nop 0
	s_nop 0
	v_lshlrev_b32_e32 v44, 16, v52
	v_and_b32_e32 v45, 0xffff0000, v52
	v_lshlrev_b32_e32 v46, 16, v53
	v_and_b32_e32 v47, 0xffff0000, v53
	v_lshlrev_b32_e32 v52, 16, v54
	v_and_b32_e32 v53, 0xffff0000, v54
	v_lshlrev_b32_e32 v54, 16, v55
	v_and_b32_e32 v55, 0xffff0000, v55
	v_pk_fma_f32 v[46:47], v[50:51], v[134:135], v[46:47]
	v_pk_fma_f32 v[44:45], v[48:49], v[132:133], v[44:45]
	v_pk_fma_f32 v[48:49], v[42:43], v[130:131], v[54:55]
	v_pk_fma_f32 v[42:43], v[40:41], v[128:129], v[52:53]
	v_cvt_pk_bf16_f32 v40, v44, v45
	v_cvt_pk_bf16_f32 v41, v46, v47
	s_nop 0
	v_cvt_pk_bf16_f32 v42, v42, v43
	v_cvt_pk_bf16_f32 v43, v48, v49
	v_mov_b64_e32 v[44:45], v[230:231]
	v_mov_b64_e32 v[46:47], v[232:233]
	v_add_co_u32_e32 v48, vcc, s68, v158
	global_store_dwordx4 v[64:65], v[40:43], off
	s_nop 0
	v_addc_co_u32_e32 v49, vcc, 0, v159, vcc
	s_nop 0
	v_lshlrev_b32_e32 v40, 16, v44
	v_and_b32_e32 v41, 0xffff0000, v44
	v_lshlrev_b32_e32 v42, 16, v45
	v_and_b32_e32 v43, 0xffff0000, v45
	v_lshlrev_b32_e32 v44, 16, v46
	v_and_b32_e32 v45, 0xffff0000, v46
	v_lshlrev_b32_e32 v46, 16, v47
	v_and_b32_e32 v47, 0xffff0000, v47
	v_pk_fma_f32 v[38:39], v[38:39], v[126:127], v[42:43]
	v_pk_fma_f32 v[36:37], v[36:37], v[124:125], v[40:41]
	v_pk_fma_f32 v[40:41], v[30:31], v[122:123], v[46:47]
	v_pk_fma_f32 v[30:31], v[28:29], v[120:121], v[44:45]
	v_cvt_pk_bf16_f32 v28, v36, v37
	v_cvt_pk_bf16_f32 v29, v38, v39
	s_nop 0
	v_cvt_pk_bf16_f32 v30, v30, v31
	v_cvt_pk_bf16_f32 v31, v40, v41
	v_mov_b64_e32 v[36:37], v[234:235]
	v_mov_b64_e32 v[38:39], v[236:237]
	v_lshl_add_u64 v[40:41], v[158:159], 0, s[20:21]
	global_store_dwordx4 v[56:57], v[28:31], off offset:256
	s_nop 0
	s_nop 0
	v_lshlrev_b32_e32 v28, 16, v36
	v_and_b32_e32 v29, 0xffff0000, v36
	v_lshlrev_b32_e32 v30, 16, v37
	v_and_b32_e32 v31, 0xffff0000, v37
	v_lshlrev_b32_e32 v36, 16, v38
	v_and_b32_e32 v37, 0xffff0000, v38
	v_lshlrev_b32_e32 v38, 16, v39
	v_and_b32_e32 v39, 0xffff0000, v39
	v_pk_fma_f32 v[30:31], v[34:35], v[134:135], v[30:31]
	v_pk_fma_f32 v[28:29], v[32:33], v[132:133], v[28:29]
	v_pk_fma_f32 v[32:33], v[26:27], v[130:131], v[38:39]
	v_pk_fma_f32 v[26:27], v[24:25], v[128:129], v[36:37]
	v_cvt_pk_bf16_f32 v24, v28, v29
	v_cvt_pk_bf16_f32 v25, v30, v31
	s_nop 0
	v_cvt_pk_bf16_f32 v26, v26, v27
	v_cvt_pk_bf16_f32 v27, v32, v33
	v_mov_b64_e32 v[28:29], v[238:239]
	v_mov_b64_e32 v[30:31], v[240:241]
	v_add_co_u32_e32 v32, vcc, s69, v158
	global_store_dwordx4 v[48:49], v[24:27], off
	s_nop 0
	v_addc_co_u32_e32 v33, vcc, 0, v159, vcc
	s_andn2_b64 vcc, exec, s[30:31]
	s_mov_b64 s[30:31], -1
	s_nop 0
	v_lshlrev_b32_e32 v24, 16, v28
	v_and_b32_e32 v25, 0xffff0000, v28
	v_lshlrev_b32_e32 v26, 16, v29
	v_and_b32_e32 v27, 0xffff0000, v29
	v_lshlrev_b32_e32 v28, 16, v30
	v_and_b32_e32 v29, 0xffff0000, v30
	v_lshlrev_b32_e32 v30, 16, v31
	v_and_b32_e32 v31, 0xffff0000, v31
	v_pk_fma_f32 v[22:23], v[22:23], v[126:127], v[26:27]
	v_pk_fma_f32 v[20:21], v[20:21], v[124:125], v[24:25]
	v_pk_fma_f32 v[24:25], v[14:15], v[122:123], v[30:31]
	v_pk_fma_f32 v[14:15], v[12:13], v[120:121], v[28:29]
	v_cvt_pk_bf16_f32 v12, v20, v21
	v_cvt_pk_bf16_f32 v13, v22, v23
	s_nop 0
	v_cvt_pk_bf16_f32 v14, v14, v15
	v_cvt_pk_bf16_f32 v15, v24, v25
	global_load_dwordx4 v[20:23], v[32:33], off
	v_lshl_add_u64 v[24:25], v[158:159], 0, s[22:23]
	global_store_dwordx4 v[40:41], v[12:15], off offset:256
	s_waitcnt vmcnt(1)
	s_nop 0
	v_lshlrev_b32_e32 v12, 16, v20
	v_and_b32_e32 v13, 0xffff0000, v20
	v_lshlrev_b32_e32 v14, 16, v21
	v_and_b32_e32 v15, 0xffff0000, v21
	v_lshlrev_b32_e32 v20, 16, v22
	v_and_b32_e32 v21, 0xffff0000, v22
	v_lshlrev_b32_e32 v22, 16, v23
	v_and_b32_e32 v23, 0xffff0000, v23
	v_pk_fma_f32 v[14:15], v[18:19], v[134:135], v[14:15]
	v_pk_fma_f32 v[12:13], v[16:17], v[132:133], v[12:13]
	v_pk_fma_f32 v[16:17], v[10:11], v[130:131], v[22:23]
	v_pk_fma_f32 v[10:11], v[8:9], v[128:129], v[20:21]
	v_cvt_pk_bf16_f32 v8, v12, v13
	v_cvt_pk_bf16_f32 v9, v14, v15
	s_nop 0
	v_cvt_pk_bf16_f32 v10, v10, v11
	v_cvt_pk_bf16_f32 v11, v16, v17
	global_load_dwordx4 v[12:15], v[24:25], off offset:256
	s_nop 0
	global_store_dwordx4 v[32:33], v[8:11], off
	s_waitcnt vmcnt(1)
	s_nop 0
	v_lshlrev_b32_e32 v8, 16, v12
	v_and_b32_e32 v9, 0xffff0000, v12
	v_lshlrev_b32_e32 v10, 16, v13
	v_and_b32_e32 v11, 0xffff0000, v13
	v_lshlrev_b32_e32 v12, 16, v14
	v_and_b32_e32 v13, 0xffff0000, v14
	v_lshlrev_b32_e32 v14, 16, v15
	v_and_b32_e32 v15, 0xffff0000, v15
	v_pk_fma_f32 v[4:5], v[4:5], v[124:125], v[8:9]
	v_pk_fma_f32 v[8:9], v[2:3], v[122:123], v[14:15]
	v_pk_fma_f32 v[2:3], v[0:1], v[120:121], v[12:13]
	v_pk_fma_f32 v[6:7], v[6:7], v[126:127], v[10:11]
	v_cvt_pk_bf16_f32 v0, v4, v5
	s_nop 0
	v_cvt_pk_bf16_f32 v1, v6, v7
	v_cvt_pk_bf16_f32 v2, v2, v3
	v_cvt_pk_bf16_f32 v3, v8, v9
	global_store_dwordx4 v[24:25], v[0:3], off offset:256
	s_cbranch_vccnz .LBB0_1680
	s_andn2_b64 vcc, exec, s[6:7]
	s_cbranch_vccnz .LBB0_1679
	s_barrier
	s_branch .LBB0_1679

; __device__ __forceinline__ unsigned cvt_pk_bf16(float lo, float hi) { unsigned r; asm volatile("v_cvt_pk_bf16_f32 %0, %1, %2" : "=v"(r) : "v"(lo), "v"(hi)); return r; }
; __device__ __forceinline__ float lo_f(unsigned w) { return __uint_as_float(w << 16); }
; __device__ __forceinline__ float hi_f(unsigned w) { return __uint_as_float(w & 0xffff0000u); }
;     __device__ __forceinline__ void operator()(f32x4 (&acc)[2][2][4][2], const Unit& u, int wr, int wc, int fr, int fq) const {
;         const int row0 = u.pm * BM + wr * 64 + fr, col0 = u.pn * BM + wc * 32 + 8 * fq;
;         const int r = u.pm < 32 ? (u.pm >> 3) : 4;
;         const float* gt = mod + (size_t)r * MODW + gate_off + col0;
;         f32x4 gv[2][2];
; #pragma unroll
;         for (int bj = 0; bj < 2; ++bj)
; #pragma unroll
;             for (int n = 0; n < 2; ++n) gv[bj][n] = *(const f32x4*)(gt + bj * HALF + 4 * n);
;         if (u.ks >= 0) {
;             float* pb = PART + ((size_t)u.ks * TC + (size_t)(row0 - TL)) * DM + col0;
; #pragma unroll
;             for (int ai = 0; ai < 2; ++ai)
; #pragma unroll
;                 for (int m = 0; m < 4; ++m)
; #pragma unroll
;                     for (int bj = 0; bj < 2; ++bj) { float* q = pb + (size_t)(ai * HALF + m * 16) * DM + bj * HALF;
;                         *(f32x4*)q = gv[bj][0] * acc[ai][bj][m][0]; *(f32x4*)(q + 4) = gv[bj][1] * acc[ai][bj][m][1]; }
;             return;
;         }
; #pragma unroll
;         for (int ai = 0; ai < 2; ++ai)
; #pragma unroll
;             for (int m = 0; m < 4; ++m) { const size_t ro = (size_t)(row0 + ai * HALF + m * 16) * DM + col0;
; #pragma unroll
;                 for (int bj = 0; bj < 2; ++bj) { f32x4 x0, x1;
;                     if (Xf32 != nullptr) { x0 = *(const f32x4*)(Xf32 + ro + bj * HALF); x1 = *(const f32x4*)(Xf32 + ro + bj * HALF + 4); }
;                     else { const u32x4 xb = *(const u32x4*)(X + ro + bj * HALF);
;                         x0 = (f32x4){lo_f(xb.x), hi_f(xb.x), lo_f(xb.y), hi_f(xb.y)}; x1 = (f32x4){lo_f(xb.z), hi_f(xb.z), lo_f(xb.w), hi_f(xb.w)}; }
;                     x0 += gv[bj][0] * acc[ai][bj][m][0]; x1 += gv[bj][1] * acc[ai][bj][m][1];
;                     u32x4 w; w.x = cvt_pk_bf16(x0[0], x0[1]); w.y = cvt_pk_bf16(x0[2], x0[3]); w.z = cvt_pk_bf16(x1[0], x1[1]); w.w = cvt_pk_bf16(x1[2], x1[3]);
;                     *(u32x4*)(X + ro + bj * HALF) = w; } }
.LBB0_1957:
	v_lshl_add_u32 v160, s69, 8, v164
	s_lshl_b64 s[30:31], s[30:31], 2
	v_lshl_or_b32 v120, s70, 8, v166
	s_add_u32 s30, s2, s30
	v_ashrrev_i32_e32 v161, 31, v160
	v_ashrrev_i32_e32 v121, 31, v120
	v_lshlrev_b64 v[122:123], 12, v[160:161]
	s_addc_u32 s31, s3, s31
	v_lshl_add_u64 v[122:123], s[8:9], 0, v[122:123]
	v_lshlrev_b64 v[162:163], 1, v[120:121]
	v_lshl_add_u64 v[120:121], v[120:121], 2, s[30:31]
	v_lshl_add_u64 v[158:159], v[122:123], 0, v[162:163]
	v_add_co_u32_e32 v122, vcc, s62, v120
	v_mov_b32_e32 v243, 0
	global_load_dwordx4 v[178:181], v[158:159], off
	global_load_dwordx4 v[182:185], v[158:159], off offset:256
	v_mov_b32_e32 v242, 0x10000
	v_lshl_add_u64 v[186:187], v[158:159], 0, v[242:243]
	global_load_dwordx4 v[190:193], v[186:187], off offset:256
	global_load_dwordx4 v[186:189], v[186:187], off
	v_mov_b32_e32 v242, 0x20000
	v_lshl_add_u64 v[194:195], v[158:159], 0, v[242:243]
	global_load_dwordx4 v[198:201], v[194:195], off offset:256
	global_load_dwordx4 v[194:197], v[194:195], off
	v_mov_b32_e32 v242, 0x30000
	v_lshl_add_u64 v[202:203], v[158:159], 0, v[242:243]
	global_load_dwordx4 v[206:209], v[202:203], off offset:256
	global_load_dwordx4 v[202:205], v[202:203], off
	v_mov_b32_e32 v242, 0x80000
	v_lshl_add_u64 v[210:211], v[158:159], 0, v[242:243]
	global_load_dwordx4 v[218:221], v[210:211], off offset:256
	global_load_dwordx4 v[210:213], v[210:211], off
	v_mov_b32_e32 v242, 0x90000
	v_lshl_add_u64 v[226:227], v[158:159], 0, v[242:243]
	global_load_dwordx4 v[230:233], v[226:227], off offset:256
	global_load_dwordx4 v[226:229], v[226:227], off
	v_mov_b32_e32 v242, 0xa0000
	v_lshl_add_u64 v[234:235], v[158:159], 0, v[242:243]
	global_load_dwordx4 v[238:241], v[234:235], off offset:256
	global_load_dwordx4 v[234:237], v[234:235], off
	s_nop 0
	v_addc_co_u32_e32 v123, vcc, 0, v121, vcc
	global_load_dwordx4 v[132:135], v[122:123], off
	v_lshl_add_u64 v[124:125], v[120:121], 0, s[16:17]
	global_load_dwordx4 v[128:131], v[124:125], off offset:16
	global_load_dwordx4 v[120:123], v[124:125], off offset:528
	s_nop 0
	global_load_dwordx4 v[124:127], v[124:125], off offset:512
	s_waitcnt vmcnt(0)
	v_mov_b64_e32 v[170:171], v[178:179]
	v_mov_b64_e32 v[172:173], v[180:181]
	v_lshlrev_b32_e32 v174, 16, v170
	v_and_b32_e32 v175, 0xffff0000, v170
	v_lshlrev_b32_e32 v170, 16, v171
	v_and_b32_e32 v171, 0xffff0000, v171
	v_lshlrev_b32_e32 v176, 16, v172
	v_and_b32_e32 v177, 0xffff0000, v172
	v_lshlrev_b32_e32 v172, 16, v173
	v_and_b32_e32 v173, 0xffff0000, v173
	v_pk_fma_f32 v[142:143], v[142:143], v[134:135], v[170:171]
	v_pk_fma_f32 v[140:141], v[140:141], v[132:133], v[174:175]
	v_pk_fma_f32 v[170:171], v[138:139], v[130:131], v[172:173]
	v_pk_fma_f32 v[138:139], v[136:137], v[128:129], v[176:177]
	v_cvt_pk_bf16_f32 v136, v140, v141
	v_cvt_pk_bf16_f32 v137, v142, v143
	s_nop 0
	v_cvt_pk_bf16_f32 v138, v138, v139
	v_cvt_pk_bf16_f32 v139, v170, v171
	v_mov_b64_e32 v[140:141], v[182:183]
	v_mov_b64_e32 v[142:143], v[184:185]
	v_or_b32_e32 v170, 16, v160
	v_ashrrev_i32_e32 v171, 31, v170
	v_lshlrev_b64 v[170:171], 12, v[170:171]
	v_lshl_add_u64 v[170:171], s[8:9], 0, v[170:171]
	global_store_dwordx4 v[158:159], v[136:139], off
	v_lshl_add_u64 v[170:171], v[170:171], 0, v[162:163]
	s_nop 0
	v_lshlrev_b32_e32 v136, 16, v140
	v_and_b32_e32 v137, 0xffff0000, v140
	v_lshlrev_b32_e32 v138, 16, v141
	v_and_b32_e32 v139, 0xffff0000, v141
	v_lshlrev_b32_e32 v140, 16, v142
	v_and_b32_e32 v141, 0xffff0000, v142
	v_lshlrev_b32_e32 v142, 16, v143
	v_and_b32_e32 v143, 0xffff0000, v143
	v_pk_fma_f32 v[114:115], v[114:115], v[126:127], v[138:139]
	v_pk_fma_f32 v[112:113], v[112:113], v[124:125], v[136:137]
	v_pk_fma_f32 v[136:137], v[110:111], v[122:123], v[142:143]
	v_pk_fma_f32 v[110:111], v[108:109], v[120:121], v[140:141]
	v_cvt_pk_bf16_f32 v108, v112, v113
	v_cvt_pk_bf16_f32 v109, v114, v115
	s_nop 0
	v_cvt_pk_bf16_f32 v110, v110, v111
	v_cvt_pk_bf16_f32 v111, v136, v137
	v_mov_b64_e32 v[112:113], v[186:187]
	v_mov_b64_e32 v[114:115], v[188:189]
	s_nop 0
	global_store_dwordx4 v[158:159], v[108:111], off offset:256
	s_nop 0
	s_nop 0
	v_lshlrev_b32_e32 v108, 16, v112
	v_and_b32_e32 v109, 0xffff0000, v112
	v_lshlrev_b32_e32 v110, 16, v113
	v_and_b32_e32 v111, 0xffff0000, v113
	v_lshlrev_b32_e32 v112, 16, v114
	v_and_b32_e32 v113, 0xffff0000, v114
	v_lshlrev_b32_e32 v114, 16, v115
	v_and_b32_e32 v115, 0xffff0000, v115
	v_pk_fma_f32 v[110:111], v[118:119], v[134:135], v[110:111]
	v_pk_fma_f32 v[108:109], v[116:117], v[132:133], v[108:109]
	v_pk_fma_f32 v[114:115], v[106:107], v[130:131], v[114:115]
	v_pk_fma_f32 v[106:107], v[104:105], v[128:129], v[112:113]
	v_cvt_pk_bf16_f32 v104, v108, v109
	v_cvt_pk_bf16_f32 v105, v110, v111
	v_or_b32_e32 v112, 32, v160
	v_cvt_pk_bf16_f32 v106, v106, v107
	v_cvt_pk_bf16_f32 v107, v114, v115
	v_mov_b64_e32 v[108:109], v[190:191]
	v_mov_b64_e32 v[110:111], v[192:193]
	v_ashrrev_i32_e32 v113, 31, v112
	v_lshlrev_b64 v[112:113], 12, v[112:113]
	v_lshl_add_u64 v[112:113], s[8:9], 0, v[112:113]
	global_store_dwordx4 v[170:171], v[104:107], off
	v_lshl_add_u64 v[112:113], v[112:113], 0, v[162:163]
	s_nop 0
	v_lshlrev_b32_e32 v104, 16, v108
	v_and_b32_e32 v105, 0xffff0000, v108
	v_lshlrev_b32_e32 v106, 16, v109
	v_and_b32_e32 v107, 0xffff0000, v109
	v_lshlrev_b32_e32 v108, 16, v110
	v_and_b32_e32 v109, 0xffff0000, v110
	v_lshlrev_b32_e32 v110, 16, v111
	v_and_b32_e32 v111, 0xffff0000, v111
	v_pk_fma_f32 v[98:99], v[98:99], v[126:127], v[106:107]
	v_pk_fma_f32 v[96:97], v[96:97], v[124:125], v[104:105]
	v_pk_fma_f32 v[104:105], v[94:95], v[122:123], v[110:111]
	v_pk_fma_f32 v[94:95], v[92:93], v[120:121], v[108:109]
; __device__ __forceinline__ unsigned cvt_pk_bf16(float lo, float hi) { unsigned r; asm volatile("v_cvt_pk_bf16_f32 %0, %1, %2" : "=v"(r) : "v"(lo), "v"(hi)); return r; }
; __device__ __forceinline__ float lo_f(unsigned w) { return __uint_as_float(w << 16); }
; __device__ __forceinline__ float hi_f(unsigned w) { return __uint_as_float(w & 0xffff0000u); }
;     __device__ __forceinline__ void operator()(f32x4 (&acc)[2][2][4][2], const Unit& u, int wr, int wc, int fr, int fq) const {
;     ...
; #pragma unroll
;         for (int ai = 0; ai < 2; ++ai)
; #pragma unroll
;             for (int m = 0; m < 4; ++m) { const size_t ro = (size_t)(row0 + ai * HALF + m * 16) * DM + col0;
; #pragma unroll
;                 for (int bj = 0; bj < 2; ++bj) { f32x4 x0, x1;
;                     if (Xf32 != nullptr) { x0 = *(const f32x4*)(Xf32 + ro + bj * HALF); x1 = *(const f32x4*)(Xf32 + ro + bj * HALF + 4); }
;                     else { const u32x4 xb = *(const u32x4*)(X + ro + bj * HALF);
;                         x0 = (f32x4){lo_f(xb.x), hi_f(xb.x), lo_f(xb.y), hi_f(xb.y)}; x1 = (f32x4){lo_f(xb.z), hi_f(xb.z), lo_f(xb.w), hi_f(xb.w)}; }
;                     x0 += gv[bj][0] * acc[ai][bj][m][0]; x1 += gv[bj][1] * acc[ai][bj][m][1];
;                     u32x4 w; w.x = cvt_pk_bf16(x0[0], x0[1]); w.y = cvt_pk_bf16(x0[2], x0[3]); w.z = cvt_pk_bf16(x1[0], x1[1]); w.w = cvt_pk_bf16(x1[2], x1[3]);
;                     *(u32x4*)(X + ro + bj * HALF) = w; } }
	v_cvt_pk_bf16_f32 v92, v96, v97
	v_cvt_pk_bf16_f32 v93, v98, v99
	s_nop 0
	v_cvt_pk_bf16_f32 v94, v94, v95
	v_cvt_pk_bf16_f32 v95, v104, v105
	v_mov_b64_e32 v[96:97], v[194:195]
	v_mov_b64_e32 v[98:99], v[196:197]
	s_nop 0
	global_store_dwordx4 v[170:171], v[92:95], off offset:256
	s_nop 0
	s_nop 0
	v_lshlrev_b32_e32 v92, 16, v96
	v_and_b32_e32 v93, 0xffff0000, v96
	v_lshlrev_b32_e32 v94, 16, v97
	v_and_b32_e32 v95, 0xffff0000, v97
	v_lshlrev_b32_e32 v96, 16, v98
	v_and_b32_e32 v97, 0xffff0000, v98
	v_lshlrev_b32_e32 v98, 16, v99
	v_and_b32_e32 v99, 0xffff0000, v99
	v_pk_fma_f32 v[94:95], v[102:103], v[134:135], v[94:95]
	v_pk_fma_f32 v[92:93], v[100:101], v[132:133], v[92:93]
	v_pk_fma_f32 v[98:99], v[90:91], v[130:131], v[98:99]
	v_pk_fma_f32 v[90:91], v[88:89], v[128:129], v[96:97]
	v_cvt_pk_bf16_f32 v88, v92, v93
	v_cvt_pk_bf16_f32 v89, v94, v95
	v_or_b32_e32 v96, 48, v160
	v_cvt_pk_bf16_f32 v90, v90, v91
	v_cvt_pk_bf16_f32 v91, v98, v99
	v_mov_b64_e32 v[92:93], v[198:199]
	v_mov_b64_e32 v[94:95], v[200:201]
	v_ashrrev_i32_e32 v97, 31, v96
	v_lshlrev_b64 v[96:97], 12, v[96:97]
	v_lshl_add_u64 v[96:97], s[8:9], 0, v[96:97]
	global_store_dwordx4 v[112:113], v[88:91], off
	v_lshl_add_u64 v[96:97], v[96:97], 0, v[162:163]
	s_nop 0
	v_lshlrev_b32_e32 v88, 16, v92
	v_and_b32_e32 v89, 0xffff0000, v92
	v_lshlrev_b32_e32 v90, 16, v93
	v_and_b32_e32 v91, 0xffff0000, v93
	v_lshlrev_b32_e32 v92, 16, v94
	v_and_b32_e32 v93, 0xffff0000, v94
	v_lshlrev_b32_e32 v94, 16, v95
	v_and_b32_e32 v95, 0xffff0000, v95
	v_pk_fma_f32 v[82:83], v[82:83], v[126:127], v[90:91]
	v_pk_fma_f32 v[80:81], v[80:81], v[124:125], v[88:89]
	v_pk_fma_f32 v[88:89], v[78:79], v[122:123], v[94:95]
	v_pk_fma_f32 v[78:79], v[76:77], v[120:121], v[92:93]
	v_cvt_pk_bf16_f32 v76, v80, v81
	v_cvt_pk_bf16_f32 v77, v82, v83
	s_nop 0
	v_cvt_pk_bf16_f32 v78, v78, v79
	v_cvt_pk_bf16_f32 v79, v88, v89
	v_mov_b64_e32 v[80:81], v[202:203]
	v_mov_b64_e32 v[82:83], v[204:205]
	s_nop 0
	global_store_dwordx4 v[112:113], v[76:79], off offset:256
	s_nop 0
	s_nop 0
	v_lshlrev_b32_e32 v76, 16, v80
	v_and_b32_e32 v77, 0xffff0000, v80
	v_lshlrev_b32_e32 v78, 16, v81
	v_and_b32_e32 v79, 0xffff0000, v81
	v_lshlrev_b32_e32 v80, 16, v82
	v_and_b32_e32 v81, 0xffff0000, v82
	v_lshlrev_b32_e32 v82, 16, v83
	v_and_b32_e32 v83, 0xffff0000, v83
	v_pk_fma_f32 v[78:79], v[86:87], v[134:135], v[78:79]
	v_pk_fma_f32 v[76:77], v[84:85], v[132:133], v[76:77]
	v_pk_fma_f32 v[82:83], v[74:75], v[130:131], v[82:83]
	v_pk_fma_f32 v[74:75], v[72:73], v[128:129], v[80:81]
	v_cvt_pk_bf16_f32 v72, v76, v77
	v_cvt_pk_bf16_f32 v73, v78, v79
	v_add_co_u32_e32 v80, vcc, s63, v158
	v_cvt_pk_bf16_f32 v74, v74, v75
	v_cvt_pk_bf16_f32 v75, v82, v83
	v_mov_b64_e32 v[76:77], v[206:207]
	v_mov_b64_e32 v[78:79], v[208:209]
	s_nop 0
	v_addc_co_u32_e32 v81, vcc, 0, v159, vcc
	global_store_dwordx4 v[96:97], v[72:75], off
	s_nop 0
	s_nop 0
	v_lshlrev_b32_e32 v72, 16, v76
	v_and_b32_e32 v73, 0xffff0000, v76
	v_lshlrev_b32_e32 v74, 16, v77
	v_and_b32_e32 v75, 0xffff0000, v77
	v_lshlrev_b32_e32 v76, 16, v78
	v_and_b32_e32 v77, 0xffff0000, v78
	v_lshlrev_b32_e32 v78, 16, v79
	v_and_b32_e32 v79, 0xffff0000, v79
	v_pk_fma_f32 v[70:71], v[70:71], v[126:127], v[74:75]
	v_pk_fma_f32 v[68:69], v[68:69], v[124:125], v[72:73]
	v_pk_fma_f32 v[72:73], v[66:67], v[122:123], v[78:79]
	v_pk_fma_f32 v[66:67], v[64:65], v[120:121], v[76:77]
	v_cvt_pk_bf16_f32 v64, v68, v69
	v_cvt_pk_bf16_f32 v65, v70, v71
	s_nop 0
	v_cvt_pk_bf16_f32 v66, v66, v67
	v_cvt_pk_bf16_f32 v67, v72, v73
	v_mov_b64_e32 v[68:69], v[210:211]
	v_mov_b64_e32 v[70:71], v[212:213]
	v_lshl_add_u64 v[72:73], v[158:159], 0, s[18:19]
	global_store_dwordx4 v[96:97], v[64:67], off offset:256
	s_nop 0
	s_nop 0
	v_lshlrev_b32_e32 v64, 16, v68
	v_and_b32_e32 v65, 0xffff0000, v68
	v_lshlrev_b32_e32 v66, 16, v69
	v_and_b32_e32 v67, 0xffff0000, v69
	v_lshlrev_b32_e32 v68, 16, v70
	v_and_b32_e32 v69, 0xffff0000, v70
	v_lshlrev_b32_e32 v70, 16, v71
	v_and_b32_e32 v71, 0xffff0000, v71
	v_pk_fma_f32 v[62:63], v[62:63], v[134:135], v[66:67]
	v_pk_fma_f32 v[60:61], v[60:61], v[132:133], v[64:65]
	v_pk_fma_f32 v[64:65], v[58:59], v[130:131], v[70:71]
	v_pk_fma_f32 v[58:59], v[56:57], v[128:129], v[68:69]
	v_cvt_pk_bf16_f32 v56, v60, v61
	v_cvt_pk_bf16_f32 v57, v62, v63
	s_nop 0
	v_cvt_pk_bf16_f32 v58, v58, v59
	v_cvt_pk_bf16_f32 v59, v64, v65
	v_mov_b64_e32 v[60:61], v[218:219]
	v_mov_b64_e32 v[62:63], v[220:221]
	v_add_co_u32_e32 v64, vcc, s64, v158
	global_store_dwordx4 v[80:81], v[56:59], off
	s_nop 0
	v_addc_co_u32_e32 v65, vcc, 0, v159, vcc
	s_nop 0
	v_lshlrev_b32_e32 v56, 16, v60
	v_and_b32_e32 v57, 0xffff0000, v60
	v_lshlrev_b32_e32 v58, 16, v61
	v_and_b32_e32 v59, 0xffff0000, v61
	v_lshlrev_b32_e32 v60, 16, v62
	v_and_b32_e32 v61, 0xffff0000, v62
	v_lshlrev_b32_e32 v62, 16, v63
	v_and_b32_e32 v63, 0xffff0000, v63
	v_pk_fma_f32 v[54:55], v[54:55], v[126:127], v[58:59]
	v_pk_fma_f32 v[52:53], v[52:53], v[124:125], v[56:57]
	v_pk_fma_f32 v[56:57], v[46:47], v[122:123], v[62:63]
	v_pk_fma_f32 v[46:47], v[44:45], v[120:121], v[60:61]
	v_cvt_pk_bf16_f32 v44, v52, v53
	v_cvt_pk_bf16_f32 v45, v54, v55
	s_nop 0
	v_cvt_pk_bf16_f32 v46, v46, v47
; __device__ __forceinline__ unsigned cvt_pk_bf16(float lo, float hi) { unsigned r; asm volatile("v_cvt_pk_bf16_f32 %0, %1, %2" : "=v"(r) : "v"(lo), "v"(hi)); return r; }
; __device__ __forceinline__ float lo_f(unsigned w) { return __uint_as_float(w << 16); }
; __device__ __forceinline__ float hi_f(unsigned w) { return __uint_as_float(w & 0xffff0000u); }
;     __device__ __forceinline__ void operator()(f32x4 (&acc)[2][2][4][2], const Unit& u, int wr, int wc, int fr, int fq) const {
;     ...
; #pragma unroll
;         for (int ai = 0; ai < 2; ++ai)
; #pragma unroll
;             for (int m = 0; m < 4; ++m) { const size_t ro = (size_t)(row0 + ai * HALF + m * 16) * DM + col0;
; #pragma unroll
;                 for (int bj = 0; bj < 2; ++bj) { f32x4 x0, x1;
;                     if (Xf32 != nullptr) { x0 = *(const f32x4*)(Xf32 + ro + bj * HALF); x1 = *(const f32x4*)(Xf32 + ro + bj * HALF + 4); }
;                     else { const u32x4 xb = *(const u32x4*)(X + ro + bj * HALF);
;                         x0 = (f32x4){lo_f(xb.x), hi_f(xb.x), lo_f(xb.y), hi_f(xb.y)}; x1 = (f32x4){lo_f(xb.z), hi_f(xb.z), lo_f(xb.w), hi_f(xb.w)}; }
;                     x0 += gv[bj][0] * acc[ai][bj][m][0]; x1 += gv[bj][1] * acc[ai][bj][m][1];
;                     u32x4 w; w.x = cvt_pk_bf16(x0[0], x0[1]); w.y = cvt_pk_bf16(x0[2], x0[3]); w.z = cvt_pk_bf16(x1[0], x1[1]); w.w = cvt_pk_bf16(x1[2], x1[3]);
;                     *(u32x4*)(X + ro + bj * HALF) = w; } }
	v_cvt_pk_bf16_f32 v47, v56, v57
	v_mov_b64_e32 v[52:53], v[226:227]
	v_mov_b64_e32 v[54:55], v[228:229]
	v_lshl_add_u64 v[56:57], v[158:159], 0, s[20:21]
	global_store_dwordx4 v[72:73], v[44:47], off offset:256
	s_nop 0
	s_nop 0
	v_lshlrev_b32_e32 v44, 16, v52
	v_and_b32_e32 v45, 0xffff0000, v52
	v_lshlrev_b32_e32 v46, 16, v53
	v_and_b32_e32 v47, 0xffff0000, v53
	v_lshlrev_b32_e32 v52, 16, v54
	v_and_b32_e32 v53, 0xffff0000, v54
	v_lshlrev_b32_e32 v54, 16, v55
	v_and_b32_e32 v55, 0xffff0000, v55
	v_pk_fma_f32 v[46:47], v[50:51], v[134:135], v[46:47]
	v_pk_fma_f32 v[44:45], v[48:49], v[132:133], v[44:45]
	v_pk_fma_f32 v[48:49], v[42:43], v[130:131], v[54:55]
	v_pk_fma_f32 v[42:43], v[40:41], v[128:129], v[52:53]
	v_cvt_pk_bf16_f32 v40, v44, v45
	v_cvt_pk_bf16_f32 v41, v46, v47
	s_nop 0
	v_cvt_pk_bf16_f32 v42, v42, v43
	v_cvt_pk_bf16_f32 v43, v48, v49
	v_mov_b64_e32 v[44:45], v[230:231]
	v_mov_b64_e32 v[46:47], v[232:233]
	v_add_co_u32_e32 v48, vcc, s65, v158
	global_store_dwordx4 v[64:65], v[40:43], off
	s_nop 0
	v_addc_co_u32_e32 v49, vcc, 0, v159, vcc
	s_nop 0
	v_lshlrev_b32_e32 v40, 16, v44
	v_and_b32_e32 v41, 0xffff0000, v44
	v_lshlrev_b32_e32 v42, 16, v45
	v_and_b32_e32 v43, 0xffff0000, v45
	v_lshlrev_b32_e32 v44, 16, v46
	v_and_b32_e32 v45, 0xffff0000, v46
	v_lshlrev_b32_e32 v46, 16, v47
	v_and_b32_e32 v47, 0xffff0000, v47
	v_pk_fma_f32 v[38:39], v[38:39], v[126:127], v[42:43]
	v_pk_fma_f32 v[36:37], v[36:37], v[124:125], v[40:41]
	v_pk_fma_f32 v[40:41], v[30:31], v[122:123], v[46:47]
	v_pk_fma_f32 v[30:31], v[28:29], v[120:121], v[44:45]
	v_cvt_pk_bf16_f32 v28, v36, v37
	v_cvt_pk_bf16_f32 v29, v38, v39
	s_nop 0
	v_cvt_pk_bf16_f32 v30, v30, v31
	v_cvt_pk_bf16_f32 v31, v40, v41
	v_mov_b64_e32 v[36:37], v[234:235]
	v_mov_b64_e32 v[38:39], v[236:237]
	v_lshl_add_u64 v[40:41], v[158:159], 0, s[22:23]
	global_store_dwordx4 v[56:57], v[28:31], off offset:256
	s_nop 0
	s_nop 0
	v_lshlrev_b32_e32 v28, 16, v36
	v_and_b32_e32 v29, 0xffff0000, v36
	v_lshlrev_b32_e32 v30, 16, v37
	v_and_b32_e32 v31, 0xffff0000, v37
	v_lshlrev_b32_e32 v36, 16, v38
	v_and_b32_e32 v37, 0xffff0000, v38
	v_lshlrev_b32_e32 v38, 16, v39
	v_and_b32_e32 v39, 0xffff0000, v39
	v_pk_fma_f32 v[30:31], v[34:35], v[134:135], v[30:31]
	v_pk_fma_f32 v[28:29], v[32:33], v[132:133], v[28:29]
	v_pk_fma_f32 v[32:33], v[26:27], v[130:131], v[38:39]
	v_pk_fma_f32 v[26:27], v[24:25], v[128:129], v[36:37]
	v_cvt_pk_bf16_f32 v24, v28, v29
	v_cvt_pk_bf16_f32 v25, v30, v31
	s_nop 0
	v_cvt_pk_bf16_f32 v26, v26, v27
	v_cvt_pk_bf16_f32 v27, v32, v33
	v_mov_b64_e32 v[28:29], v[238:239]
	v_mov_b64_e32 v[30:31], v[240:241]
	v_add_co_u32_e32 v32, vcc, s66, v158
	global_store_dwordx4 v[48:49], v[24:27], off
	s_nop 0
	v_addc_co_u32_e32 v33, vcc, 0, v159, vcc
	s_and_b64 vcc, exec, s[4:5]
	s_mov_b64 s[4:5], -1
	s_nop 0
	v_lshlrev_b32_e32 v24, 16, v28
	v_and_b32_e32 v25, 0xffff0000, v28
	v_lshlrev_b32_e32 v26, 16, v29
	v_and_b32_e32 v27, 0xffff0000, v29
	v_lshlrev_b32_e32 v28, 16, v30
	v_and_b32_e32 v29, 0xffff0000, v30
	v_lshlrev_b32_e32 v30, 16, v31
	v_and_b32_e32 v31, 0xffff0000, v31
	v_pk_fma_f32 v[22:23], v[22:23], v[126:127], v[26:27]
	v_pk_fma_f32 v[20:21], v[20:21], v[124:125], v[24:25]
	v_pk_fma_f32 v[24:25], v[14:15], v[122:123], v[30:31]
	v_pk_fma_f32 v[14:15], v[12:13], v[120:121], v[28:29]
	v_cvt_pk_bf16_f32 v12, v20, v21
	v_cvt_pk_bf16_f32 v13, v22, v23
	s_nop 0
	v_cvt_pk_bf16_f32 v14, v14, v15
	v_cvt_pk_bf16_f32 v15, v24, v25
	global_load_dwordx4 v[20:23], v[32:33], off
	v_lshl_add_u64 v[24:25], v[158:159], 0, s[24:25]
	global_store_dwordx4 v[40:41], v[12:15], off offset:256
	s_waitcnt vmcnt(1)
	s_nop 0
	v_lshlrev_b32_e32 v12, 16, v20
	v_and_b32_e32 v13, 0xffff0000, v20
	v_lshlrev_b32_e32 v14, 16, v21
	v_and_b32_e32 v15, 0xffff0000, v21
	v_lshlrev_b32_e32 v20, 16, v22
	v_and_b32_e32 v21, 0xffff0000, v22
	v_lshlrev_b32_e32 v22, 16, v23
	v_and_b32_e32 v23, 0xffff0000, v23
	v_pk_fma_f32 v[14:15], v[18:19], v[134:135], v[14:15]
	v_pk_fma_f32 v[12:13], v[16:17], v[132:133], v[12:13]
	v_pk_fma_f32 v[16:17], v[10:11], v[130:131], v[22:23]
	v_pk_fma_f32 v[10:11], v[8:9], v[128:129], v[20:21]
	v_cvt_pk_bf16_f32 v8, v12, v13
	v_cvt_pk_bf16_f32 v9, v14, v15
	s_nop 0
	v_cvt_pk_bf16_f32 v10, v10, v11
	v_cvt_pk_bf16_f32 v11, v16, v17
	global_load_dwordx4 v[12:15], v[24:25], off offset:256
	s_nop 0
	global_store_dwordx4 v[32:33], v[8:11], off
	s_waitcnt vmcnt(1)
	s_nop 0
	v_lshlrev_b32_e32 v8, 16, v12
	v_and_b32_e32 v9, 0xffff0000, v12
	v_lshlrev_b32_e32 v10, 16, v13
	v_and_b32_e32 v11, 0xffff0000, v13
	v_lshlrev_b32_e32 v12, 16, v14
	v_and_b32_e32 v13, 0xffff0000, v14
	v_lshlrev_b32_e32 v14, 16, v15
	v_and_b32_e32 v15, 0xffff0000, v15
	v_pk_fma_f32 v[4:5], v[4:5], v[124:125], v[8:9]
	v_pk_fma_f32 v[8:9], v[2:3], v[122:123], v[14:15]
	v_pk_fma_f32 v[2:3], v[0:1], v[120:121], v[12:13]
	v_pk_fma_f32 v[6:7], v[6:7], v[126:127], v[10:11]
	v_cvt_pk_bf16_f32 v0, v4, v5
	s_nop 0
	v_cvt_pk_bf16_f32 v1, v6, v7
	v_cvt_pk_bf16_f32 v2, v2, v3
	v_cvt_pk_bf16_f32 v3, v8, v9
	global_store_dwordx4 v[24:25], v[0:3], off offset:256
	s_cbranch_vccnz .LBB0_1938
	s_andn2_b64 vcc, exec, s[6:7]
	s_cbranch_vccnz .LBB0_1937
	s_barrier
	s_branch .LBB0_1937
